# lever 9 (doc 7.12, serial chain before the wave-uniform rescale branch): canonicalising self-max instructions removed from the row-max chain in the four hot attention bodies (13 VALU)
# baseline (speedup 1.0000x reference)
.LBB0_589:
	s_add_i32 s30, s21, 0xffff0000
	s_and_b32 s30, s30, 0xc000
	s_add_i32 s42, s30, 0
	v_add_u32_e32 v0, s42, v210
	s_sub_i32 s43, s28, 64
	ds_read_b128 v[6:9], v0
	ds_read_b128 v[10:13], v0 offset:8192
	v_cvt_f32_u32_e32 v0, s43
	v_add_u32_e32 v14, s42, v211
	ds_read_b128 v[224:227], v14
	ds_read_b128 v[228:231], v14 offset:8192
	s_add_i32 s36, s21, 0xfffec000
	v_sub_f32_e32 v0, v0, v205
	v_fma_f32 v112, v166, v0, -v169
	v_add_f32_e32 v128, v168, v112
	v_add_f32_e32 v129, v166, v128
	v_add_f32_e32 v130, v167, v128
	v_add_f32_e32 v131, v186, v128
	v_add_f32_e32 v132, v187, v128
	v_add_f32_e32 v133, v166, v132
	v_add_f32_e32 v134, v167, v132
	v_add_f32_e32 v135, v186, v132
	v_add_f32_e32 v136, v187, v132
	v_add_f32_e32 v137, v166, v136
	v_add_f32_e32 v138, v167, v136
	v_add_f32_e32 v139, v186, v136
	v_add_f32_e32 v140, v187, v136
	v_add_f32_e32 v141, v166, v140
	v_add_f32_e32 v142, v167, v140
	v_add_f32_e32 v143, v186, v140
	v_add_f32_e32 v113, v166, v112
	v_add_f32_e32 v114, v167, v112
	v_add_f32_e32 v115, v186, v112
	v_add_f32_e32 v116, v187, v112
	v_add_f32_e32 v117, v166, v116
	v_add_f32_e32 v118, v167, v116
	v_add_f32_e32 v119, v186, v116
	v_add_f32_e32 v120, v187, v116
	v_add_f32_e32 v121, v166, v120
	v_add_f32_e32 v122, v167, v120
	v_add_f32_e32 v123, v186, v120
	v_add_f32_e32 v124, v187, v120
	v_add_f32_e32 v125, v166, v124
	v_add_f32_e32 v126, v167, v124
	v_add_f32_e32 v127, v186, v124
	s_waitcnt lgkmcnt(2)
	v_mfma_f32_32x32x16_bf16 v[128:143], v[10:13], v[144:147], v[128:143]
	v_add_u32_e32 v0, s42, v212
	s_and_b32 s36, s36, 0x8000
	v_exp_f32_e32 v96, v96
	v_exp_f32_e32 v14, v97
	v_exp_f32_e32 v80, v80
	v_exp_f32_e32 v98, v98
	v_exp_f32_e32 v82, v82
	v_mfma_f32_32x32x16_bf16 v[112:127], v[6:9], v[144:147], v[112:127]
	ds_read_b128 v[6:9], v0
	ds_read_b128 v[10:13], v0 offset:8192
	v_add_u32_e32 v0, s42, v213
	v_exp_f32_e32 v248, v99
	v_exp_f32_e32 v250, v83
	v_exp_f32_e32 v83, v84
	v_exp_f32_e32 v84, v86
	v_exp_f32_e32 v196, v103
	s_waitcnt lgkmcnt(3)
	v_mfma_f32_32x32x16_bf16 v[112:127], v[224:227], v[148:151], v[112:127]
	ds_read_b128 v[224:227], v0
	ds_read_b128 v[232:235], v0 offset:8192
	v_add_u32_e32 v0, s36, v204
	ds_read_b128 v[236:239], v0
	ds_read_b128 v[240:243], v0 offset:4096
	v_exp_f32_e32 v86, v106
	v_exp_f32_e32 v198, v105
	v_exp_f32_e32 v106, v89
	v_exp_f32_e32 v164, v107
	s_waitcnt lgkmcnt(6)
	v_mfma_f32_32x32x16_bf16 v[128:143], v[228:231], v[148:151], v[128:143]
	ds_read_b128 v[228:231], v0 offset:8192
	ds_read_b128 v[244:247], v0 offset:12288
	v_exp_f32_e32 v0, v81
	v_exp_f32_e32 v81, v104
	v_exp_f32_e32 v104, v87
	v_exp_f32_e32 v87, v90
	v_exp_f32_e32 v160, v91
	v_exp_f32_e32 v89, v92
	s_waitcnt lgkmcnt(7)
	v_mfma_f32_32x32x16_bf16 v[112:127], v[6:9], v[152:155], v[112:127]
	v_exp_f32_e32 v8, v100
	v_exp_f32_e32 v9, v102
	v_exp_f32_e32 v90, v110
	v_exp_f32_e32 v91, v94
	v_exp_f32_e32 v162, v109
	v_exp_f32_e32 v200, v111
	v_exp_f32_e32 v110, v95
	s_waitcnt lgkmcnt(6)
	v_mfma_f32_32x32x16_bf16 v[128:143], v[10:13], v[152:155], v[128:143]
	v_cvt_pk_bf16_f32 v6, v96, v14
	v_add_f32_e32 v15, v96, v80
	v_add_f32_e32 v249, v98, v82
	v_add_f32_e32 v197, v9, v84
	v_add_f32_e32 v165, v86, v87
	v_add_f32_e32 v201, v90, v91
	v_cvt_pk_bf16_f32 v7, v98, v248
	s_waitcnt lgkmcnt(5)
	v_mfma_f32_32x32x16_bf16 v[112:127], v[224:227], v[156:159], v[112:127]
	v_exp_f32_e32 v224, v101
	v_exp_f32_e32 v226, v85
	v_exp_f32_e32 v85, v88
	v_exp_f32_e32 v88, v108
	v_exp_f32_e32 v108, v93
	v_add_f32_e32 v225, v8, v83
	v_add_f32_e32 v199, v81, v85
	s_waitcnt lgkmcnt(4)
	v_mfma_f32_32x32x16_bf16 v[128:143], v[232:235], v[156:159], v[128:143]
	v_add_f32_e32 v163, v88, v89
	v_cvt_pk_bf16_f32 v8, v8, v224
	v_cvt_pk_bf16_f32 v9, v9, v196
	v_cvt_pk_bf16_f32 v10, v81, v198
	v_cvt_pk_bf16_f32 v11, v86, v164
	v_cvt_pk_bf16_f32 v12, v88, v162
	v_cvt_pk_bf16_f32 v13, v90, v200
	v_cvt_pk_bf16_f32 v80, v80, v0
	v_cvt_pk_bf16_f32 v81, v82, v250
	v_cvt_pk_bf16_f32 v82, v83, v226
	v_cvt_pk_bf16_f32 v83, v84, v104
	v_cvt_pk_bf16_f32 v84, v85, v106
	v_cvt_pk_bf16_f32 v85, v87, v160
	v_cvt_pk_bf16_f32 v86, v89, v108
	v_cvt_pk_bf16_f32 v87, v91, v110
	v_add_f32_e32 v14, v14, v0
	v_add_f32_e32 v15, v15, v1
	v_add_u32_e32 v100, s36, v220
	v_add_f32_e32 v251, v14, v15
	v_add_f32_e32 v14, v248, v250
	v_add_f32_e32 v15, v249, v251
	s_waitcnt lgkmcnt(3)
	v_mfma_f32_32x32x16_bf16 v[64:79], v[236:239], v[6:9], v[64:79]
	v_add_f32_e32 v227, v14, v15
	v_add_f32_e32 v14, v224, v226
	v_add_f32_e32 v15, v225, v227
	ds_read_b128 v[88:91], v100
	ds_read_b128 v[92:95], v100 offset:4096
	ds_read_b128 v[96:99], v100 offset:8192
	ds_read_b128 v[100:103], v100 offset:12288
	v_add_f32_e32 v105, v14, v15
	v_add_f32_e32 v14, v196, v104
	v_add_f32_e32 v15, v197, v105
	s_waitcnt lgkmcnt(6)
	v_mfma_f32_32x32x16_bf16 v[48:63], v[240:243], v[6:9], v[48:63]
	v_add_f32_e32 v107, v14, v15
	v_add_f32_e32 v14, v198, v106
	v_add_f32_e32 v15, v199, v107
	s_nop 0
	v_add_f32_e32 v161, v14, v15
	v_add_f32_e32 v14, v164, v160
	v_add_f32_e32 v15, v165, v161
	s_waitcnt lgkmcnt(5)
	v_mfma_f32_32x32x16_bf16 v[32:47], v[228:231], v[6:9], v[32:47]
	v_add_f32_e32 v109, v14, v15
	v_add_f32_e32 v14, v162, v108
	v_add_f32_e32 v15, v163, v109
	s_nop 0
	v_add_f32_e32 v111, v14, v15
	v_add_f32_e32 v14, v200, v110
	v_add_f32_e32 v15, v201, v111
	s_waitcnt lgkmcnt(4)
	v_mfma_f32_32x32x16_bf16 v[16:31], v[244:247], v[6:9], v[16:31]
	v_add_f32_e32 v0, v14, v15
	v_add_f32_e32 v6, v184, v0
	s_waitcnt lgkmcnt(3)
	v_mfma_f32_32x32x16_bf16 v[64:79], v[88:91], v[10:13], v[64:79]
	v_add_u32_e32 v0, s36, v221
	s_waitcnt lgkmcnt(2)
	v_mfma_f32_32x32x16_bf16 v[48:63], v[92:95], v[10:13], v[48:63]
	s_waitcnt lgkmcnt(1)
	v_mfma_f32_32x32x16_bf16 v[32:47], v[96:99], v[10:13], v[32:47]
	ds_read_b128 v[88:91], v0
	ds_read_b128 v[92:95], v0 offset:4096
	ds_read_b128 v[96:99], v0 offset:8192
	ds_read_b128 v[104:107], v0 offset:12288
	s_waitcnt lgkmcnt(4)
	v_mfma_f32_32x32x16_bf16 v[16:31], v[100:103], v[10:13], v[16:31]
	v_add_u32_e32 v0, s36, v222
	ds_read_b128 v[8:11], v0
	ds_read_b128 v[12:15], v0 offset:4096
	s_waitcnt lgkmcnt(5)
	v_mfma_f32_32x32x16_bf16 v[64:79], v[88:91], v[80:83], v[64:79]
	ds_read_b128 v[88:91], v0 offset:8192
	ds_read_b128 v[100:103], v0 offset:12288
	v_max_f32_e32 v0, v113, v129
	v_max3_f32 v7, v112, v128, v114
	v_max3_f32 v0, v0, v115, v131
	v_max3_f32 v7, v7, v130, v116
	v_max3_f32 v0, v0, v117, v133
	s_waitcnt lgkmcnt(6)
	v_mfma_f32_32x32x16_bf16 v[48:63], v[92:95], v[80:83], v[48:63]
	v_max3_f32 v7, v7, v132, v118
	v_max3_f32 v0, v0, v119, v135
	v_max3_f32 v7, v7, v134, v120
	v_max3_f32 v0, v0, v121, v137
	v_max3_f32 v7, v7, v136, v122
	v_max3_f32 v0, v0, v123, v139
	v_max3_f32 v7, v7, v138, v124
	s_waitcnt lgkmcnt(5)
	v_mfma_f32_32x32x16_bf16 v[32:47], v[96:99], v[80:83], v[32:47]
	v_max3_f32 v0, v0, v125, v141
	v_max3_f32 v7, v7, v140, v126
	v_max3_f32 v0, v0, v127, v143
	v_max3_f32 v0, v7, v142, v0
	v_mov_b32_e32 v7, v0
	s_nop 1
	v_permlane32_swap_b32_e32 v0, v7
	s_waitcnt lgkmcnt(4)
	v_mfma_f32_32x32x16_bf16 v[16:31], v[104:107], v[80:83], v[16:31]
	s_waitcnt lgkmcnt(3)
	v_mfma_f32_32x32x16_bf16 v[64:79], v[8:11], v[84:87], v[64:79]
	v_max_f32_e32 v0, v0, v7
	v_cmp_lt_f32_e32 vcc, s93, v0
	s_waitcnt lgkmcnt(2)
	v_mfma_f32_32x32x16_bf16 v[48:63], v[12:15], v[84:87], v[48:63]
	s_waitcnt lgkmcnt(1)
	v_mfma_f32_32x32x16_bf16 v[32:47], v[88:91], v[84:87], v[32:47]
	s_waitcnt lgkmcnt(0)
	v_mfma_f32_32x32x16_bf16 v[16:31], v[100:103], v[84:87], v[16:31]
	s_cbranch_vccz .LBB0_591
	v_max_f32_e32 v0, v0, v0
	v_max_f32_e32 v7, 0, v0
	v_exp_f32_e64 v0, -v7
	v_add_f32_e32 v169, v169, v7
	v_sub_f32_e32 v127, v127, v7
	v_sub_f32_e32 v126, v126, v7
	v_pk_mul_f32 v[78:79], v[78:79], v[0:1] op_sel_hi:[1,0]
	v_pk_mul_f32 v[76:77], v[76:77], v[0:1] op_sel_hi:[1,0]
	v_pk_mul_f32 v[74:75], v[74:75], v[0:1] op_sel_hi:[1,0]
	v_pk_mul_f32 v[72:73], v[72:73], v[0:1] op_sel_hi:[1,0]
	v_pk_mul_f32 v[70:71], v[70:71], v[0:1] op_sel_hi:[1,0]
	v_pk_mul_f32 v[68:69], v[68:69], v[0:1] op_sel_hi:[1,0]
	v_pk_mul_f32 v[66:67], v[66:67], v[0:1] op_sel_hi:[1,0]
	v_pk_mul_f32 v[64:65], v[64:65], v[0:1] op_sel_hi:[1,0]
	v_pk_mul_f32 v[62:63], v[62:63], v[0:1] op_sel_hi:[1,0]
	v_pk_mul_f32 v[60:61], v[60:61], v[0:1] op_sel_hi:[1,0]
	v_pk_mul_f32 v[58:59], v[58:59], v[0:1] op_sel_hi:[1,0]
	v_pk_mul_f32 v[56:57], v[56:57], v[0:1] op_sel_hi:[1,0]
	v_pk_mul_f32 v[54:55], v[54:55], v[0:1] op_sel_hi:[1,0]
	v_pk_mul_f32 v[52:53], v[52:53], v[0:1] op_sel_hi:[1,0]
	v_pk_mul_f32 v[50:51], v[50:51], v[0:1] op_sel_hi:[1,0]
	v_pk_mul_f32 v[48:49], v[48:49], v[0:1] op_sel_hi:[1,0]
	v_pk_mul_f32 v[46:47], v[0:1], v[46:47] op_sel_hi:[0,1]
	v_pk_mul_f32 v[44:45], v[0:1], v[44:45] op_sel_hi:[0,1]
	v_pk_mul_f32 v[42:43], v[0:1], v[42:43] op_sel_hi:[0,1]
	v_pk_mul_f32 v[40:41], v[0:1], v[40:41] op_sel_hi:[0,1]
	v_pk_mul_f32 v[38:39], v[0:1], v[38:39] op_sel_hi:[0,1]
	v_pk_mul_f32 v[36:37], v[0:1], v[36:37] op_sel_hi:[0,1]
	v_pk_mul_f32 v[34:35], v[0:1], v[34:35] op_sel_hi:[0,1]
	v_pk_mul_f32 v[32:33], v[0:1], v[32:33] op_sel_hi:[0,1]
	v_pk_mul_f32 v[30:31], v[0:1], v[30:31] op_sel_hi:[0,1]
	v_pk_mul_f32 v[28:29], v[0:1], v[28:29] op_sel_hi:[0,1]
	v_pk_mul_f32 v[26:27], v[0:1], v[26:27] op_sel_hi:[0,1]
	v_pk_mul_f32 v[24:25], v[0:1], v[24:25] op_sel_hi:[0,1]
	v_pk_mul_f32 v[22:23], v[0:1], v[22:23] op_sel_hi:[0,1]
	v_pk_mul_f32 v[20:21], v[0:1], v[20:21] op_sel_hi:[0,1]
	v_pk_mul_f32 v[18:19], v[0:1], v[18:19] op_sel_hi:[0,1]
	v_pk_mul_f32 v[16:17], v[0:1], v[16:17] op_sel_hi:[0,1]
	v_sub_f32_e32 v125, v125, v7
	v_sub_f32_e32 v124, v124, v7
	v_sub_f32_e32 v123, v123, v7
	v_sub_f32_e32 v122, v122, v7
	v_sub_f32_e32 v121, v121, v7
	v_sub_f32_e32 v120, v120, v7
	v_sub_f32_e32 v119, v119, v7
	v_sub_f32_e32 v118, v118, v7
	v_sub_f32_e32 v117, v117, v7
	v_sub_f32_e32 v116, v116, v7
	v_sub_f32_e32 v115, v115, v7
	v_sub_f32_e32 v114, v114, v7
	v_sub_f32_e32 v113, v113, v7
	v_sub_f32_e32 v112, v112, v7
	v_sub_f32_e32 v143, v143, v7
	v_sub_f32_e32 v142, v142, v7
	v_sub_f32_e32 v141, v141, v7
	v_sub_f32_e32 v140, v140, v7
	v_sub_f32_e32 v139, v139, v7
	v_sub_f32_e32 v138, v138, v7
	v_sub_f32_e32 v137, v137, v7
	v_sub_f32_e32 v136, v136, v7
	v_sub_f32_e32 v135, v135, v7
	v_sub_f32_e32 v134, v134, v7
	v_sub_f32_e32 v133, v133, v7
	v_sub_f32_e32 v132, v132, v7
	v_sub_f32_e32 v131, v131, v7
	v_sub_f32_e32 v130, v130, v7
	v_sub_f32_e32 v129, v129, v7
	v_sub_f32_e32 v128, v128, v7
	v_mul_f32_e32 v6, v6, v0

.LBB0_595:
	s_add_i32 s36, s21, 0xffff4000
	s_and_b32 s36, s36, 0x8000
	s_add_i32 s36, s36, 0
	v_add_u32_e32 v0, s36, v210
	ds_read_b128 v[2:5], v0
	ds_read_b128 v[8:11], v0 offset:8192
	v_cvt_f32_u32_e32 v0, s28
	v_add_u32_e32 v7, s36, v211
	ds_read_b128 v[12:15], v7
	ds_read_b128 v[224:227], v7 offset:8192
	v_sub_f32_e32 v0, v0, v205
	v_fma_f32 v96, v166, v0, -v169
	v_add_f32_e32 v97, v166, v96
	v_add_f32_e32 v98, v167, v96
	v_add_f32_e32 v99, v186, v96
	v_add_f32_e32 v100, v187, v96
	v_add_f32_e32 v101, v166, v100
	v_add_f32_e32 v102, v167, v100
	v_add_f32_e32 v103, v186, v100
	v_add_f32_e32 v104, v187, v100
	v_add_f32_e32 v105, v166, v104
	v_add_f32_e32 v106, v167, v104
	v_add_f32_e32 v107, v186, v104
	v_add_f32_e32 v108, v187, v104
	v_add_f32_e32 v109, v166, v108
	v_add_f32_e32 v110, v167, v108
	v_add_f32_e32 v111, v186, v108
	v_add_f32_e32 v80, v168, v96
	v_add_f32_e32 v81, v166, v80
	v_add_f32_e32 v82, v167, v80
	v_add_f32_e32 v83, v186, v80
	v_add_f32_e32 v84, v187, v80
	v_add_f32_e32 v85, v166, v84
	v_add_f32_e32 v86, v167, v84
	v_add_f32_e32 v87, v186, v84
	v_add_f32_e32 v88, v187, v84
	v_add_f32_e32 v89, v166, v88
	v_add_f32_e32 v90, v167, v88
	v_add_f32_e32 v91, v186, v88
	v_add_f32_e32 v92, v187, v88
	v_add_f32_e32 v93, v166, v92
	v_add_f32_e32 v94, v167, v92
	v_add_f32_e32 v95, v186, v92
	s_waitcnt lgkmcnt(3)
	v_mfma_f32_32x32x16_bf16 v[96:111], v[2:5], v[144:147], v[96:111]
	v_add_u32_e32 v0, s36, v212
	v_exp_f32_e32 v7, v112
	v_exp_f32_e32 v112, v128
	v_exp_f32_e32 v160, v129
	v_exp_f32_e32 v116, v116
	v_exp_f32_e32 v128, v132
	v_exp_f32_e32 v132, v115
	s_waitcnt lgkmcnt(2)
	v_mfma_f32_32x32x16_bf16 v[80:95], v[8:11], v[144:147], v[80:95]
	ds_read_b128 v[2:5], v0
	ds_read_b128 v[8:11], v0 offset:8192
	v_add_u32_e32 v0, s36, v213
	v_exp_f32_e32 v162, v131
	v_exp_f32_e32 v115, v134
	v_exp_f32_e32 v134, v117
	v_exp_f32_e32 v164, v133
	v_exp_f32_e32 v198, v119
	s_waitcnt lgkmcnt(3)
	v_mfma_f32_32x32x16_bf16 v[96:111], v[12:15], v[148:151], v[96:111]
	ds_read_b128 v[12:15], v0
	ds_read_b128 v[228:231], v0 offset:8192
	v_add_u32_e32 v0, s30, v204
	ds_read_b128 v[232:235], v0
	ds_read_b128 v[236:239], v0 offset:4096
	v_exp_f32_e32 v117, v136
	v_exp_f32_e32 v196, v135
	v_exp_f32_e32 v136, v121
	v_exp_f32_e32 v200, v137
	s_waitcnt lgkmcnt(6)
	v_mfma_f32_32x32x16_bf16 v[80:95], v[224:227], v[148:151], v[80:95]
	ds_read_b128 v[224:227], v0 offset:8192
	ds_read_b128 v[240:243], v0 offset:12288
	v_exp_f32_e32 v0, v113
	v_exp_f32_e32 v113, v114
	v_exp_f32_e32 v114, v130
	v_exp_f32_e32 v244, v139
	v_exp_f32_e32 v119, v140
	v_exp_f32_e32 v140, v125
	s_waitcnt lgkmcnt(7)
	v_mfma_f32_32x32x16_bf16 v[96:111], v[2:5], v[152:155], v[96:111]
	v_exp_f32_e32 v5, v118
	v_exp_f32_e32 v118, v138
	v_exp_f32_e32 v138, v123
	v_exp_f32_e32 v246, v141
	v_exp_f32_e32 v248, v143
	v_add_f32_e32 v161, v112, v7
	v_add_f32_e32 v163, v114, v113
	s_waitcnt lgkmcnt(6)
	v_mfma_f32_32x32x16_bf16 v[80:95], v[8:11], v[152:155], v[80:95]
	v_add_f32_e32 v165, v128, v116
	v_add_f32_e32 v197, v115, v5
	v_cvt_pk_bf16_f32 v2, v7, v0
	v_cvt_pk_bf16_f32 v3, v113, v132
	v_cvt_pk_bf16_f32 v4, v116, v134
	v_cvt_pk_bf16_f32 v5, v5, v198
	v_cvt_pk_bf16_f32 v113, v118, v244
	s_waitcnt lgkmcnt(5)
	v_mfma_f32_32x32x16_bf16 v[96:111], v[12:15], v[156:159], v[96:111]
	v_exp_f32_e32 v12, v120
	v_exp_f32_e32 v13, v122
	v_exp_f32_e32 v14, v124
	v_exp_f32_e32 v15, v126
	v_exp_f32_e32 v120, v142
	v_exp_f32_e32 v142, v127
	v_add_f32_e32 v201, v117, v12
	s_waitcnt lgkmcnt(4)
	v_mfma_f32_32x32x16_bf16 v[80:95], v[228:231], v[156:159], v[80:95]
	v_add_f32_e32 v245, v118, v13
	v_add_f32_e32 v247, v119, v14
	v_add_f32_e32 v249, v120, v15
	v_cvt_pk_bf16_f32 v8, v12, v136
	v_cvt_pk_bf16_f32 v9, v13, v138
	v_cvt_pk_bf16_f32 v10, v14, v140
	v_cvt_pk_bf16_f32 v11, v15, v142
	v_cvt_pk_bf16_f32 v12, v112, v160
	v_cvt_pk_bf16_f32 v13, v114, v162
	v_cvt_pk_bf16_f32 v14, v128, v164
	v_cvt_pk_bf16_f32 v15, v115, v196
	v_cvt_pk_bf16_f32 v112, v117, v200
	v_cvt_pk_bf16_f32 v114, v119, v246
	v_cvt_pk_bf16_f32 v115, v120, v248
	v_add_f32_e32 v160, v160, v0
	v_add_f32_e32 v161, v161, v1
	v_add_u32_e32 v7, s30, v220
	v_add_f32_e32 v161, v160, v161
	v_add_f32_e32 v160, v160, v160
	v_mov_b32_e32 v133, v161
	v_add_f32_e32 v132, v162, v132
	v_add_f32_e32 v133, v163, v133
	s_waitcnt lgkmcnt(3)
	v_mfma_f32_32x32x16_bf16 v[64:79], v[232:235], v[2:5], v[64:79]
	v_add_f32_e32 v135, v132, v133
	v_add_f32_e32 v132, v164, v134
	v_add_f32_e32 v133, v165, v135
	ds_read_b128 v[116:119], v7
	ds_read_b128 v[120:123], v7 offset:4096
	ds_read_b128 v[124:127], v7 offset:8192
	ds_read_b128 v[128:131], v7 offset:12288
	v_add_f32_e32 v199, v132, v133
	v_add_f32_e32 v132, v196, v198
	v_add_f32_e32 v133, v197, v199
	s_waitcnt lgkmcnt(6)
	v_mfma_f32_32x32x16_bf16 v[48:63], v[236:239], v[2:5], v[48:63]
	v_add_f32_e32 v137, v132, v133
	v_add_f32_e32 v132, v200, v136
	v_add_f32_e32 v133, v201, v137
	s_nop 0
	v_add_f32_e32 v139, v132, v133
	v_add_f32_e32 v132, v244, v138
	v_add_f32_e32 v133, v245, v139
	s_waitcnt lgkmcnt(5)
	v_mfma_f32_32x32x16_bf16 v[32:47], v[224:227], v[2:5], v[32:47]
	v_add_f32_e32 v141, v132, v133
	v_add_f32_e32 v132, v246, v140
	v_add_f32_e32 v133, v247, v141
	s_nop 0
	v_add_f32_e32 v143, v132, v133
	v_add_f32_e32 v132, v248, v142
	v_add_f32_e32 v133, v249, v143
	s_waitcnt lgkmcnt(4)
	v_mfma_f32_32x32x16_bf16 v[16:31], v[240:243], v[2:5], v[16:31]
	v_add_f32_e32 v0, v132, v133
	v_add_f32_e32 v184, v6, v0
	s_waitcnt lgkmcnt(3)
	v_mfma_f32_32x32x16_bf16 v[64:79], v[116:119], v[8:11], v[64:79]
	v_add_u32_e32 v0, s30, v221
	s_waitcnt lgkmcnt(2)
	v_mfma_f32_32x32x16_bf16 v[48:63], v[120:123], v[8:11], v[48:63]
	s_waitcnt lgkmcnt(1)
	v_mfma_f32_32x32x16_bf16 v[32:47], v[124:127], v[8:11], v[32:47]
	ds_read_b128 v[2:5], v0
	ds_read_b128 v[116:119], v0 offset:4096
	ds_read_b128 v[120:123], v0 offset:8192
	ds_read_b128 v[124:127], v0 offset:12288
	s_waitcnt lgkmcnt(4)
	v_mfma_f32_32x32x16_bf16 v[16:31], v[128:131], v[8:11], v[16:31]
	v_add_u32_e32 v0, s30, v222
	ds_read_b128 v[6:9], v0
	ds_read_b128 v[128:131], v0 offset:4096
	s_waitcnt lgkmcnt(5)
	v_mfma_f32_32x32x16_bf16 v[64:79], v[2:5], v[12:15], v[64:79]
	ds_read_b128 v[2:5], v0 offset:8192
	ds_read_b128 v[132:135], v0 offset:12288
	v_max_f32_e32 v0, v97, v81
	v_max3_f32 v10, v96, v80, v98
	v_max3_f32 v0, v0, v99, v83
	v_max3_f32 v10, v10, v82, v100
	v_max3_f32 v0, v0, v101, v85
	s_waitcnt lgkmcnt(6)
	v_mfma_f32_32x32x16_bf16 v[48:63], v[116:119], v[12:15], v[48:63]
	v_max3_f32 v10, v10, v84, v102
	v_max3_f32 v0, v0, v103, v87
	v_max3_f32 v10, v10, v86, v104
	v_max3_f32 v0, v0, v105, v89
	v_max3_f32 v10, v10, v88, v106
	v_max3_f32 v0, v0, v107, v91
	v_max3_f32 v10, v10, v90, v108
	s_waitcnt lgkmcnt(5)
	v_mfma_f32_32x32x16_bf16 v[32:47], v[120:123], v[12:15], v[32:47]
	v_max3_f32 v0, v0, v109, v93
	v_max3_f32 v10, v10, v92, v110
	v_max3_f32 v0, v0, v111, v95
	v_max3_f32 v0, v10, v94, v0
	v_mov_b32_e32 v10, v0
	s_nop 1
	v_permlane32_swap_b32_e32 v0, v10
	s_waitcnt lgkmcnt(4)
	v_mfma_f32_32x32x16_bf16 v[16:31], v[124:127], v[12:15], v[16:31]
	s_waitcnt lgkmcnt(3)
	v_mfma_f32_32x32x16_bf16 v[64:79], v[6:9], v[112:115], v[64:79]
	s_waitcnt lgkmcnt(2)
	v_mfma_f32_32x32x16_bf16 v[48:63], v[128:131], v[112:115], v[48:63]
	s_waitcnt lgkmcnt(1)
	v_mfma_f32_32x32x16_bf16 v[32:47], v[2:5], v[112:115], v[32:47]
	v_max_f32_e32 v2, v10, v10
	v_max_f32_e32 v0, v0, v2
	v_cmp_lt_f32_e32 vcc, s93, v0
	s_waitcnt lgkmcnt(0)
	v_mfma_f32_32x32x16_bf16 v[16:31], v[132:135], v[112:115], v[16:31]
	s_cbranch_vccz .LBB0_597
	v_max_f32_e32 v0, v0, v0
	v_max_f32_e32 v2, 0, v0
	v_exp_f32_e64 v0, -v2
	v_add_f32_e32 v169, v169, v2
	v_sub_f32_e32 v111, v111, v2
	v_sub_f32_e32 v110, v110, v2
	v_pk_mul_f32 v[78:79], v[78:79], v[0:1] op_sel_hi:[1,0]
	v_pk_mul_f32 v[76:77], v[76:77], v[0:1] op_sel_hi:[1,0]
	v_pk_mul_f32 v[74:75], v[74:75], v[0:1] op_sel_hi:[1,0]
	v_pk_mul_f32 v[72:73], v[72:73], v[0:1] op_sel_hi:[1,0]
	v_pk_mul_f32 v[70:71], v[70:71], v[0:1] op_sel_hi:[1,0]
	v_pk_mul_f32 v[68:69], v[68:69], v[0:1] op_sel_hi:[1,0]
	v_pk_mul_f32 v[66:67], v[66:67], v[0:1] op_sel_hi:[1,0]
	v_pk_mul_f32 v[64:65], v[64:65], v[0:1] op_sel_hi:[1,0]
	v_pk_mul_f32 v[62:63], v[62:63], v[0:1] op_sel_hi:[1,0]
	v_pk_mul_f32 v[60:61], v[60:61], v[0:1] op_sel_hi:[1,0]
	v_pk_mul_f32 v[58:59], v[58:59], v[0:1] op_sel_hi:[1,0]
	v_pk_mul_f32 v[56:57], v[56:57], v[0:1] op_sel_hi:[1,0]
	v_pk_mul_f32 v[54:55], v[54:55], v[0:1] op_sel_hi:[1,0]
	v_pk_mul_f32 v[52:53], v[52:53], v[0:1] op_sel_hi:[1,0]
	v_pk_mul_f32 v[50:51], v[50:51], v[0:1] op_sel_hi:[1,0]
	v_pk_mul_f32 v[48:49], v[48:49], v[0:1] op_sel_hi:[1,0]
	v_pk_mul_f32 v[46:47], v[0:1], v[46:47] op_sel_hi:[0,1]
	v_pk_mul_f32 v[44:45], v[0:1], v[44:45] op_sel_hi:[0,1]
	v_pk_mul_f32 v[42:43], v[0:1], v[42:43] op_sel_hi:[0,1]
	v_pk_mul_f32 v[40:41], v[0:1], v[40:41] op_sel_hi:[0,1]
	v_pk_mul_f32 v[38:39], v[0:1], v[38:39] op_sel_hi:[0,1]
	v_pk_mul_f32 v[36:37], v[0:1], v[36:37] op_sel_hi:[0,1]
	v_pk_mul_f32 v[34:35], v[0:1], v[34:35] op_sel_hi:[0,1]
	v_pk_mul_f32 v[32:33], v[0:1], v[32:33] op_sel_hi:[0,1]
	v_pk_mul_f32 v[30:31], v[0:1], v[30:31] op_sel_hi:[0,1]
	v_pk_mul_f32 v[28:29], v[0:1], v[28:29] op_sel_hi:[0,1]
	v_pk_mul_f32 v[26:27], v[0:1], v[26:27] op_sel_hi:[0,1]
	v_pk_mul_f32 v[24:25], v[0:1], v[24:25] op_sel_hi:[0,1]
	v_pk_mul_f32 v[22:23], v[0:1], v[22:23] op_sel_hi:[0,1]
	v_pk_mul_f32 v[20:21], v[0:1], v[20:21] op_sel_hi:[0,1]
	v_pk_mul_f32 v[18:19], v[0:1], v[18:19] op_sel_hi:[0,1]
	v_pk_mul_f32 v[16:17], v[0:1], v[16:17] op_sel_hi:[0,1]
	v_sub_f32_e32 v109, v109, v2
	v_sub_f32_e32 v108, v108, v2
	v_sub_f32_e32 v107, v107, v2
	v_sub_f32_e32 v106, v106, v2
	v_sub_f32_e32 v105, v105, v2
	v_sub_f32_e32 v104, v104, v2
	v_sub_f32_e32 v103, v103, v2
	v_sub_f32_e32 v102, v102, v2
	v_sub_f32_e32 v101, v101, v2
	v_sub_f32_e32 v100, v100, v2
	v_sub_f32_e32 v99, v99, v2
	v_sub_f32_e32 v98, v98, v2
	v_sub_f32_e32 v97, v97, v2
	v_sub_f32_e32 v96, v96, v2
	v_sub_f32_e32 v95, v95, v2
	v_sub_f32_e32 v94, v94, v2
	v_sub_f32_e32 v93, v93, v2
	v_sub_f32_e32 v92, v92, v2
	v_sub_f32_e32 v91, v91, v2
	v_sub_f32_e32 v90, v90, v2
	v_sub_f32_e32 v89, v89, v2
	v_sub_f32_e32 v88, v88, v2
	v_sub_f32_e32 v87, v87, v2
	v_sub_f32_e32 v86, v86, v2
	v_sub_f32_e32 v85, v85, v2
	v_sub_f32_e32 v84, v84, v2
	v_sub_f32_e32 v83, v83, v2
	v_sub_f32_e32 v82, v82, v2
	v_sub_f32_e32 v81, v81, v2
	v_sub_f32_e32 v80, v80, v2
	v_mul_f32_e32 v184, v184, v0

.LBB0_641:
	s_add_i32 s19, s20, 0xffff0000
	s_and_b32 s19, s19, 0xc000
	s_add_i32 s28, s19, 0
	v_add_u32_e32 v0, s28, v210
	s_sub_i32 s30, s18, 64
	ds_read_b128 v[186:189], v0
	ds_read_b128 v[216:219], v0 offset:8192
	v_cvt_f32_i32_e32 v0, s30
	v_add_u32_e32 v112, s28, v211
	ds_read_b128 v[220:223], v112
	ds_read_b128 v[224:227], v112 offset:8192
	s_add_i32 s21, s20, 0xfffec000
	v_sub_f32_e32 v0, v0, v205
	v_fma_f32 v112, v0, -v166, -v169
	v_add_f32_e32 v128, v15, v112
	v_add_f32_e32 v116, v14, v112
	v_add_f32_e32 v132, v14, v128
	v_add_f32_e32 v120, v14, v116
	v_add_f32_e32 v136, v14, v132
	v_add_f32_e32 v124, v14, v120
	v_add_f32_e32 v140, v14, v136
	v_sub_f32_e32 v113, v112, v166
	v_sub_f32_e32 v129, v128, v166
	v_sub_f32_e32 v117, v116, v166
	v_sub_f32_e32 v133, v132, v166
	v_sub_f32_e32 v121, v120, v166
	v_sub_f32_e32 v137, v136, v166
	v_sub_f32_e32 v125, v124, v166
	v_sub_f32_e32 v141, v140, v166
	v_add_f32_e32 v114, v2, v112
	v_add_f32_e32 v115, v3, v112
	v_add_f32_e32 v130, v2, v128
	v_add_f32_e32 v131, v3, v128
	v_add_f32_e32 v118, v2, v116
	v_add_f32_e32 v119, v3, v116
	v_add_f32_e32 v134, v2, v132
	v_add_f32_e32 v135, v3, v132
	v_add_f32_e32 v122, v2, v120
	v_add_f32_e32 v123, v3, v120
	v_add_f32_e32 v138, v2, v136
	v_add_f32_e32 v139, v3, v136
	v_add_f32_e32 v126, v2, v124
	v_add_f32_e32 v127, v3, v124
	v_add_f32_e32 v142, v2, v140
	v_add_f32_e32 v143, v3, v140
	s_waitcnt lgkmcnt(3)
	v_mfma_f32_32x32x16_bf16 v[112:127], v[186:189], v[144:147], v[112:127]
	v_add_u32_e32 v0, s28, v212
	ds_read_b128 v[228:231], v0
	ds_read_b128 v[232:235], v0 offset:8192
	v_add_u32_e32 v0, s28, v213
	ds_read_b128 v[186:189], v0
	ds_read_b128 v[236:239], v0 offset:8192
	s_and_b32 s21, s21, 0xc000
	v_add_u32_e32 v0, s21, v204
	ds_read_b128 v[240:243], v0
	ds_read_b128 v[244:247], v0 offset:4096
	s_waitcnt lgkmcnt(8)
	v_mfma_f32_32x32x16_bf16 v[128:143], v[216:219], v[144:147], v[128:143]
	ds_read_b128 v[216:219], v0 offset:8192
	ds_read_b128 v[248:251], v0 offset:12288
	v_exp_f32_e32 v96, v96
	v_exp_f32_e32 v165, v80
	v_exp_f32_e32 v160, v97
	v_exp_f32_e32 v0, v81
	v_exp_f32_e32 v81, v98
	v_exp_f32_e32 v97, v82
	s_waitcnt lgkmcnt(9)
	v_mfma_f32_32x32x16_bf16 v[112:127], v[220:223], v[148:151], v[112:127]
	v_exp_f32_e32 v82, v100
	v_exp_f32_e32 v98, v84
	v_exp_f32_e32 v162, v99
	v_exp_f32_e32 v164, v83
	v_exp_f32_e32 v83, v102
	v_exp_f32_e32 v99, v86
	v_exp_f32_e32 v182, v101
	s_waitcnt lgkmcnt(8)
	v_mfma_f32_32x32x16_bf16 v[128:143], v[224:227], v[148:151], v[128:143]
	v_exp_f32_e32 v190, v85
	v_exp_f32_e32 v84, v104
	v_exp_f32_e32 v100, v88
	v_exp_f32_e32 v196, v103
	v_exp_f32_e32 v198, v87
	v_exp_f32_e32 v200, v105
	v_exp_f32_e32 v220, v89
	s_waitcnt lgkmcnt(7)
	v_mfma_f32_32x32x16_bf16 v[112:127], v[228:231], v[152:155], v[112:127]
	v_exp_f32_e32 v85, v106
	v_exp_f32_e32 v101, v90
	v_exp_f32_e32 v86, v108
	v_exp_f32_e32 v102, v92
	v_exp_f32_e32 v87, v110
	v_exp_f32_e32 v103, v94
	v_exp_f32_e32 v222, v109
	s_waitcnt lgkmcnt(6)
	v_mfma_f32_32x32x16_bf16 v[128:143], v[232:235], v[152:155], v[128:143]
	v_exp_f32_e32 v224, v93
	v_exp_f32_e32 v226, v111
	v_exp_f32_e32 v228, v95
	v_add_f32_e32 v161, v96, v165
	v_add_f32_e32 v163, v81, v97
	v_add_f32_e32 v183, v82, v98
	v_add_f32_e32 v197, v83, v99
	s_waitcnt lgkmcnt(5)
	v_mfma_f32_32x32x16_bf16 v[112:127], v[186:189], v[156:159], v[112:127]
	v_exp_f32_e32 v186, v107
	v_exp_f32_e32 v188, v91
	v_add_f32_e32 v201, v84, v100
	v_add_f32_e32 v187, v85, v101
	v_add_f32_e32 v223, v86, v102
	v_add_f32_e32 v227, v87, v103
	v_cvt_pk_bf16_f32 v80, v96, v160
	s_waitcnt lgkmcnt(4)
	v_mfma_f32_32x32x16_bf16 v[128:143], v[236:239], v[156:159], v[128:143]
	v_cvt_pk_bf16_f32 v81, v81, v162
	v_cvt_pk_bf16_f32 v82, v82, v182
	v_cvt_pk_bf16_f32 v83, v83, v196
	v_cvt_pk_bf16_f32 v84, v84, v200
	v_cvt_pk_bf16_f32 v85, v85, v186
	v_cvt_pk_bf16_f32 v86, v86, v222
	v_cvt_pk_bf16_f32 v87, v87, v226
	v_cvt_pk_bf16_f32 v88, v165, v0
	v_cvt_pk_bf16_f32 v89, v97, v164
	v_cvt_pk_bf16_f32 v90, v98, v190
	v_cvt_pk_bf16_f32 v91, v99, v198
	v_cvt_pk_bf16_f32 v92, v100, v220
	v_cvt_pk_bf16_f32 v93, v101, v188
	v_cvt_pk_bf16_f32 v94, v102, v224
	v_cvt_pk_bf16_f32 v95, v103, v228
	v_add_f32_e32 v160, v160, v0
	v_add_f32_e32 v161, v161, v1
	v_add_u32_e32 v108, s21, v167
	v_add_f32_e32 v165, v160, v161
	v_add_f32_e32 v160, v162, v164
	v_add_f32_e32 v161, v163, v165
	s_waitcnt lgkmcnt(3)
	v_mfma_f32_32x32x16_bf16 v[64:79], v[240:243], v[80:83], v[64:79]
	v_add_f32_e32 v191, v160, v161
	v_add_f32_e32 v160, v182, v190
	v_add_f32_e32 v161, v183, v191
	ds_read_b128 v[96:99], v108
	ds_read_b128 v[100:103], v108 offset:4096
	ds_read_b128 v[104:107], v108 offset:8192
	ds_read_b128 v[108:111], v108 offset:12288
	v_add_f32_e32 v199, v160, v161
	v_add_f32_e32 v160, v196, v198
	v_add_f32_e32 v161, v197, v199
	s_waitcnt lgkmcnt(6)
	v_mfma_f32_32x32x16_bf16 v[48:63], v[244:247], v[80:83], v[48:63]
	v_add_f32_e32 v221, v160, v161
	v_add_f32_e32 v160, v200, v220
	v_add_f32_e32 v161, v201, v221
	s_nop 0
	v_add_f32_e32 v189, v160, v161
	v_add_f32_e32 v160, v186, v188
	v_add_f32_e32 v161, v187, v189
	s_waitcnt lgkmcnt(5)
	v_mfma_f32_32x32x16_bf16 v[32:47], v[216:219], v[80:83], v[32:47]
	v_add_f32_e32 v225, v160, v161
	v_add_f32_e32 v160, v222, v224
	v_add_f32_e32 v161, v223, v225
	s_nop 0
	v_add_f32_e32 v229, v160, v161
	v_add_f32_e32 v160, v226, v228
	v_add_f32_e32 v161, v227, v229
	s_waitcnt lgkmcnt(4)
	v_mfma_f32_32x32x16_bf16 v[16:31], v[248:251], v[80:83], v[16:31]
	v_add_f32_e32 v0, v160, v161
	v_add_f32_e32 v178, v184, v0
	s_waitcnt lgkmcnt(3)
	v_mfma_f32_32x32x16_bf16 v[64:79], v[96:99], v[84:87], v[64:79]
	v_add_u32_e32 v0, s21, v168
	s_waitcnt lgkmcnt(2)
	v_mfma_f32_32x32x16_bf16 v[48:63], v[100:103], v[84:87], v[48:63]
	s_waitcnt lgkmcnt(1)
	v_mfma_f32_32x32x16_bf16 v[32:47], v[104:107], v[84:87], v[32:47]
	ds_read_b128 v[80:83], v0
	ds_read_b128 v[96:99], v0 offset:4096
	ds_read_b128 v[100:103], v0 offset:8192
	ds_read_b128 v[104:107], v0 offset:12288
	s_waitcnt lgkmcnt(4)
	v_mfma_f32_32x32x16_bf16 v[16:31], v[108:111], v[84:87], v[16:31]
	v_add_u32_e32 v0, s21, v180
	ds_read_b128 v[84:87], v0
	ds_read_b128 v[108:111], v0 offset:4096
	s_waitcnt lgkmcnt(5)
	v_mfma_f32_32x32x16_bf16 v[64:79], v[80:83], v[88:91], v[64:79]
	ds_read_b128 v[80:83], v0 offset:8192
	ds_read_b128 v[182:185], v0 offset:12288
	v_max_f32_e32 v0, v113, v129
	v_max3_f32 v160, v112, v128, v114
	v_max3_f32 v0, v0, v115, v131
	v_max3_f32 v160, v160, v130, v116
	v_max3_f32 v0, v0, v117, v133
	s_waitcnt lgkmcnt(6)
	v_mfma_f32_32x32x16_bf16 v[48:63], v[96:99], v[88:91], v[48:63]
	v_max3_f32 v96, v160, v132, v118
	v_max3_f32 v0, v0, v119, v135
	v_max3_f32 v96, v96, v134, v120
	v_max3_f32 v0, v0, v121, v137
	v_max3_f32 v96, v96, v136, v122
	v_max3_f32 v0, v0, v123, v139
	v_max3_f32 v96, v96, v138, v124
	s_waitcnt lgkmcnt(5)
	v_mfma_f32_32x32x16_bf16 v[32:47], v[100:103], v[88:91], v[32:47]
	v_max3_f32 v0, v0, v125, v141
	v_max3_f32 v96, v96, v140, v126
	v_max3_f32 v0, v0, v127, v143
	v_max3_f32 v0, v96, v142, v0
	v_mov_b32_e32 v96, v0
	s_nop 1
	v_permlane32_swap_b32_e32 v0, v96
	s_waitcnt lgkmcnt(4)
	v_mfma_f32_32x32x16_bf16 v[16:31], v[104:107], v[88:91], v[16:31]
	s_waitcnt lgkmcnt(3)
	v_mfma_f32_32x32x16_bf16 v[64:79], v[84:87], v[92:95], v[64:79]
	s_waitcnt lgkmcnt(2)
	v_mfma_f32_32x32x16_bf16 v[48:63], v[108:111], v[92:95], v[48:63]
	s_waitcnt lgkmcnt(1)
	v_mfma_f32_32x32x16_bf16 v[32:47], v[80:83], v[92:95], v[32:47]
	v_max_f32_e32 v80, v96, v96
	v_max_f32_e32 v0, v0, v80
	v_cmp_lt_f32_e32 vcc, s93, v0
	s_waitcnt lgkmcnt(0)
	v_mfma_f32_32x32x16_bf16 v[16:31], v[182:185], v[92:95], v[16:31]
	s_cbranch_vccz .LBB0_643
	v_max_f32_e32 v0, v0, v0
	v_max_f32_e32 v80, 0, v0
	v_exp_f32_e64 v0, -v80
	v_add_f32_e32 v169, v169, v80
	v_sub_f32_e32 v127, v127, v80
	v_sub_f32_e32 v126, v126, v80
	v_pk_mul_f32 v[78:79], v[78:79], v[0:1] op_sel_hi:[1,0]
	v_pk_mul_f32 v[76:77], v[76:77], v[0:1] op_sel_hi:[1,0]
	v_pk_mul_f32 v[74:75], v[74:75], v[0:1] op_sel_hi:[1,0]
	v_pk_mul_f32 v[72:73], v[72:73], v[0:1] op_sel_hi:[1,0]
	v_pk_mul_f32 v[70:71], v[70:71], v[0:1] op_sel_hi:[1,0]
	v_pk_mul_f32 v[68:69], v[68:69], v[0:1] op_sel_hi:[1,0]
	v_pk_mul_f32 v[66:67], v[66:67], v[0:1] op_sel_hi:[1,0]
	v_pk_mul_f32 v[64:65], v[64:65], v[0:1] op_sel_hi:[1,0]
	v_pk_mul_f32 v[62:63], v[62:63], v[0:1] op_sel_hi:[1,0]
	v_pk_mul_f32 v[60:61], v[60:61], v[0:1] op_sel_hi:[1,0]
	v_pk_mul_f32 v[58:59], v[58:59], v[0:1] op_sel_hi:[1,0]
	v_pk_mul_f32 v[56:57], v[56:57], v[0:1] op_sel_hi:[1,0]
	v_pk_mul_f32 v[54:55], v[54:55], v[0:1] op_sel_hi:[1,0]
	v_pk_mul_f32 v[52:53], v[52:53], v[0:1] op_sel_hi:[1,0]
	v_pk_mul_f32 v[50:51], v[50:51], v[0:1] op_sel_hi:[1,0]
	v_pk_mul_f32 v[48:49], v[48:49], v[0:1] op_sel_hi:[1,0]
	v_pk_mul_f32 v[46:47], v[0:1], v[46:47] op_sel_hi:[0,1]
	v_pk_mul_f32 v[44:45], v[0:1], v[44:45] op_sel_hi:[0,1]
	v_pk_mul_f32 v[42:43], v[0:1], v[42:43] op_sel_hi:[0,1]
	v_pk_mul_f32 v[40:41], v[0:1], v[40:41] op_sel_hi:[0,1]
	v_pk_mul_f32 v[38:39], v[0:1], v[38:39] op_sel_hi:[0,1]
	v_pk_mul_f32 v[36:37], v[0:1], v[36:37] op_sel_hi:[0,1]
	v_pk_mul_f32 v[34:35], v[0:1], v[34:35] op_sel_hi:[0,1]
	v_pk_mul_f32 v[32:33], v[0:1], v[32:33] op_sel_hi:[0,1]
	v_pk_mul_f32 v[30:31], v[0:1], v[30:31] op_sel_hi:[0,1]
	v_pk_mul_f32 v[28:29], v[0:1], v[28:29] op_sel_hi:[0,1]
	v_pk_mul_f32 v[26:27], v[0:1], v[26:27] op_sel_hi:[0,1]
	v_pk_mul_f32 v[24:25], v[0:1], v[24:25] op_sel_hi:[0,1]
	v_pk_mul_f32 v[22:23], v[0:1], v[22:23] op_sel_hi:[0,1]
	v_pk_mul_f32 v[20:21], v[0:1], v[20:21] op_sel_hi:[0,1]
	v_pk_mul_f32 v[18:19], v[0:1], v[18:19] op_sel_hi:[0,1]
	v_pk_mul_f32 v[16:17], v[0:1], v[16:17] op_sel_hi:[0,1]
	v_sub_f32_e32 v125, v125, v80
	v_sub_f32_e32 v124, v124, v80
	v_sub_f32_e32 v123, v123, v80
	v_sub_f32_e32 v122, v122, v80
	v_sub_f32_e32 v121, v121, v80
	v_sub_f32_e32 v120, v120, v80
	v_sub_f32_e32 v119, v119, v80
	v_sub_f32_e32 v118, v118, v80
	v_sub_f32_e32 v117, v117, v80
	v_sub_f32_e32 v116, v116, v80
	v_sub_f32_e32 v115, v115, v80
	v_sub_f32_e32 v114, v114, v80
	v_sub_f32_e32 v113, v113, v80
	v_sub_f32_e32 v112, v112, v80
	v_sub_f32_e32 v143, v143, v80
	v_sub_f32_e32 v142, v142, v80
	v_sub_f32_e32 v141, v141, v80
	v_sub_f32_e32 v140, v140, v80
	v_sub_f32_e32 v139, v139, v80
	v_sub_f32_e32 v138, v138, v80
	v_sub_f32_e32 v137, v137, v80
	v_sub_f32_e32 v136, v136, v80
	v_sub_f32_e32 v135, v135, v80
	v_sub_f32_e32 v134, v134, v80
	v_sub_f32_e32 v133, v133, v80
	v_sub_f32_e32 v132, v132, v80
	v_sub_f32_e32 v131, v131, v80
	v_sub_f32_e32 v130, v130, v80
	v_sub_f32_e32 v129, v129, v80
	v_sub_f32_e32 v128, v128, v80
	v_mul_f32_e32 v178, v178, v0

.LBB0_653:
	s_add_i32 s21, s20, 0xffff4000
	s_and_b32 s21, s21, 0xc000
	s_add_i32 s21, s21, 0
	v_add_u32_e32 v0, s21, v210
	ds_read_b128 v[8:11], v0
	ds_read_b128 v[182:185], v0 offset:8192
	v_cvt_f32_i32_e32 v0, s18
	v_add_u32_e32 v80, s21, v211
	ds_read_b128 v[186:189], v80
	ds_read_b128 v[216:219], v80 offset:8192
	v_sub_f32_e32 v0, v0, v205
	v_fma_f32 v96, v0, -v166, -v169
	v_add_f32_e32 v80, v15, v96
	v_add_f32_e32 v100, v14, v96
	v_add_f32_e32 v84, v14, v80
	v_add_f32_e32 v104, v14, v100
	v_add_f32_e32 v88, v14, v84
	v_add_f32_e32 v108, v14, v104
	v_add_f32_e32 v92, v14, v88
	v_sub_f32_e32 v97, v96, v166
	v_sub_f32_e32 v81, v80, v166
	v_sub_f32_e32 v101, v100, v166
	v_sub_f32_e32 v85, v84, v166
	v_sub_f32_e32 v105, v104, v166
	v_sub_f32_e32 v89, v88, v166
	v_sub_f32_e32 v109, v108, v166
	v_sub_f32_e32 v93, v92, v166
	v_add_f32_e32 v98, v2, v96
	v_add_f32_e32 v99, v3, v96
	v_add_f32_e32 v82, v2, v80
	v_add_f32_e32 v83, v3, v80
	v_add_f32_e32 v102, v2, v100
	v_add_f32_e32 v103, v3, v100
	v_add_f32_e32 v86, v2, v84
	v_add_f32_e32 v87, v3, v84
	v_add_f32_e32 v106, v2, v104
	v_add_f32_e32 v107, v3, v104
	v_add_f32_e32 v90, v2, v88
	v_add_f32_e32 v91, v3, v88
	v_add_f32_e32 v110, v2, v108
	v_add_f32_e32 v111, v3, v108
	v_add_f32_e32 v94, v2, v92
	v_add_f32_e32 v95, v3, v92
	s_waitcnt lgkmcnt(3)
	v_mfma_f32_32x32x16_bf16 v[96:111], v[8:11], v[144:147], v[96:111]
	v_add_u32_e32 v0, s21, v212
	ds_read_b128 v[220:223], v0
	ds_read_b128 v[224:227], v0 offset:8192
	v_add_u32_e32 v0, s21, v213
	ds_read_b128 v[228:231], v0
	ds_read_b128 v[232:235], v0 offset:8192
	v_add_u32_e32 v0, s19, v204
	ds_read_b128 v[8:11], v0
	ds_read_b128 v[236:239], v0 offset:4096
	ds_read_b128 v[240:243], v0 offset:8192
	ds_read_b128 v[244:247], v0 offset:12288
	s_waitcnt lgkmcnt(10)
	v_mfma_f32_32x32x16_bf16 v[80:95], v[182:185], v[144:147], v[80:95]
	v_exp_f32_e32 v112, v112
	v_exp_f32_e32 v128, v128
	v_exp_f32_e32 v0, v113
	v_exp_f32_e32 v160, v129
	v_exp_f32_e32 v113, v114
	v_exp_f32_e32 v129, v130
	v_exp_f32_e32 v114, v116
	s_waitcnt lgkmcnt(9)
	v_mfma_f32_32x32x16_bf16 v[96:111], v[186:189], v[148:151], v[96:111]
	v_exp_f32_e32 v130, v132
	v_exp_f32_e32 v164, v115
	v_exp_f32_e32 v162, v131
	v_exp_f32_e32 v115, v118
	v_exp_f32_e32 v131, v134
	v_exp_f32_e32 v184, v117
	v_exp_f32_e32 v182, v133
	s_waitcnt lgkmcnt(8)
	v_mfma_f32_32x32x16_bf16 v[80:95], v[216:219], v[148:151], v[80:95]
	v_exp_f32_e32 v188, v119
	v_exp_f32_e32 v186, v135
	v_exp_f32_e32 v116, v120
	v_exp_f32_e32 v132, v136
	v_exp_f32_e32 v117, v122
	v_exp_f32_e32 v133, v138
	v_exp_f32_e32 v196, v121
	s_waitcnt lgkmcnt(7)
	v_mfma_f32_32x32x16_bf16 v[96:111], v[220:223], v[152:155], v[96:111]
	v_exp_f32_e32 v190, v137
	v_exp_f32_e32 v118, v124
	v_exp_f32_e32 v134, v140
	v_exp_f32_e32 v200, v123
	v_exp_f32_e32 v198, v139
	v_exp_f32_e32 v119, v126
	v_exp_f32_e32 v135, v142
	s_waitcnt lgkmcnt(6)
	v_mfma_f32_32x32x16_bf16 v[80:95], v[224:227], v[152:155], v[80:95]
	v_exp_f32_e32 v218, v125
	v_exp_f32_e32 v216, v141
	v_exp_f32_e32 v222, v127
	v_exp_f32_e32 v220, v143
	v_add_f32_e32 v161, v128, v112
	v_add_f32_e32 v163, v129, v113
	v_add_f32_e32 v183, v130, v114
	s_waitcnt lgkmcnt(5)
	v_mfma_f32_32x32x16_bf16 v[96:111], v[228:231], v[156:159], v[96:111]
	v_add_f32_e32 v187, v131, v115
	v_add_f32_e32 v191, v132, v116
	v_add_f32_e32 v199, v133, v117
	v_add_f32_e32 v217, v134, v118
	v_add_f32_e32 v221, v135, v119
	v_cvt_pk_bf16_f32 v112, v112, v0
	v_cvt_pk_bf16_f32 v113, v113, v164
	s_waitcnt lgkmcnt(4)
	v_mfma_f32_32x32x16_bf16 v[80:95], v[232:235], v[156:159], v[80:95]
	v_cvt_pk_bf16_f32 v114, v114, v184
	v_cvt_pk_bf16_f32 v115, v115, v188
	v_cvt_pk_bf16_f32 v116, v116, v196
	v_cvt_pk_bf16_f32 v117, v117, v200
	v_cvt_pk_bf16_f32 v118, v118, v218
	v_cvt_pk_bf16_f32 v119, v119, v222
	v_cvt_pk_bf16_f32 v120, v128, v160
	v_cvt_pk_bf16_f32 v121, v129, v162
	v_cvt_pk_bf16_f32 v122, v130, v182
	v_cvt_pk_bf16_f32 v123, v131, v186
	v_cvt_pk_bf16_f32 v124, v132, v190
	v_cvt_pk_bf16_f32 v125, v133, v198
	v_cvt_pk_bf16_f32 v126, v134, v216
	v_cvt_pk_bf16_f32 v127, v135, v220
	v_add_f32_e32 v160, v160, v0
	v_add_f32_e32 v161, v161, v1
	s_waitcnt lgkmcnt(3)
	v_mfma_f32_32x32x16_bf16 v[64:79], v[8:11], v[112:115], v[64:79]
	v_add_f32_e32 v165, v160, v161
	v_add_f32_e32 v8, v162, v164
	v_add_f32_e32 v9, v163, v165
	v_add_u32_e32 v140, s19, v167
	v_add_f32_e32 v185, v8, v9
	v_add_f32_e32 v8, v182, v184
	v_add_f32_e32 v9, v183, v185
	s_waitcnt lgkmcnt(2)
	v_mfma_f32_32x32x16_bf16 v[48:63], v[236:239], v[112:115], v[48:63]
	v_add_f32_e32 v189, v8, v9
	v_add_f32_e32 v8, v186, v188
	v_add_f32_e32 v9, v187, v189
	ds_read_b128 v[128:131], v140
	ds_read_b128 v[132:135], v140 offset:4096
	ds_read_b128 v[136:139], v140 offset:8192
	ds_read_b128 v[140:143], v140 offset:12288
	v_add_f32_e32 v197, v8, v9
	v_add_f32_e32 v8, v190, v196
	v_add_f32_e32 v9, v191, v197
	s_waitcnt lgkmcnt(5)
	v_mfma_f32_32x32x16_bf16 v[32:47], v[240:243], v[112:115], v[32:47]
	v_add_f32_e32 v201, v8, v9
	v_add_f32_e32 v8, v198, v200
	v_add_f32_e32 v9, v199, v201
	s_nop 0
	v_add_f32_e32 v219, v8, v9
	v_add_f32_e32 v8, v216, v218
	v_add_f32_e32 v9, v217, v219
	s_waitcnt lgkmcnt(4)
	v_mfma_f32_32x32x16_bf16 v[16:31], v[244:247], v[112:115], v[16:31]
	v_add_f32_e32 v223, v8, v9
	v_add_f32_e32 v8, v220, v222
	v_add_f32_e32 v9, v221, v223
	s_nop 0
	v_add_f32_e32 v0, v8, v9
	v_add_f32_e32 v184, v178, v0
	s_waitcnt lgkmcnt(3)
	v_mfma_f32_32x32x16_bf16 v[64:79], v[128:131], v[116:119], v[64:79]
	v_add_u32_e32 v0, s19, v168
	s_waitcnt lgkmcnt(2)
	v_mfma_f32_32x32x16_bf16 v[48:63], v[132:135], v[116:119], v[48:63]
	ds_read_b128 v[8:11], v0
	ds_read_b128 v[112:115], v0 offset:4096
	ds_read_b128 v[128:131], v0 offset:8192
	ds_read_b128 v[132:135], v0 offset:12288
	s_waitcnt lgkmcnt(5)
	v_mfma_f32_32x32x16_bf16 v[32:47], v[136:139], v[116:119], v[32:47]
	s_waitcnt lgkmcnt(4)
	v_mfma_f32_32x32x16_bf16 v[16:31], v[140:143], v[116:119], v[16:31]
	v_add_u32_e32 v0, s19, v180
	ds_read_b128 v[116:119], v0
	ds_read_b128 v[136:139], v0 offset:4096
	s_waitcnt lgkmcnt(5)
	v_mfma_f32_32x32x16_bf16 v[64:79], v[8:11], v[120:123], v[64:79]
	ds_read_b128 v[8:11], v0 offset:8192
	ds_read_b128 v[140:143], v0 offset:12288
	v_max_f32_e32 v0, v97, v81
	v_max3_f32 v160, v96, v80, v98
	v_max3_f32 v0, v0, v99, v83
	v_max3_f32 v160, v160, v82, v100
	v_max3_f32 v0, v0, v101, v85
	s_waitcnt lgkmcnt(6)
	v_mfma_f32_32x32x16_bf16 v[48:63], v[112:115], v[120:123], v[48:63]
	v_max3_f32 v112, v160, v84, v102
	v_max3_f32 v0, v0, v103, v87
	v_max3_f32 v112, v112, v86, v104
	v_max3_f32 v0, v0, v105, v89
	v_max3_f32 v112, v112, v88, v106
	v_max3_f32 v0, v0, v107, v91
	v_max3_f32 v112, v112, v90, v108
	s_waitcnt lgkmcnt(5)
	v_mfma_f32_32x32x16_bf16 v[32:47], v[128:131], v[120:123], v[32:47]
	v_max3_f32 v0, v0, v109, v93
	v_max3_f32 v112, v112, v92, v110
	v_max3_f32 v0, v0, v111, v95
	v_max3_f32 v0, v112, v94, v0
	v_mov_b32_e32 v112, v0
	s_nop 1
	v_permlane32_swap_b32_e32 v0, v112
	s_waitcnt lgkmcnt(4)
	v_mfma_f32_32x32x16_bf16 v[16:31], v[132:135], v[120:123], v[16:31]
	s_waitcnt lgkmcnt(3)
	v_mfma_f32_32x32x16_bf16 v[64:79], v[116:119], v[124:127], v[64:79]
	s_waitcnt lgkmcnt(2)
	v_mfma_f32_32x32x16_bf16 v[48:63], v[136:139], v[124:127], v[48:63]
	s_waitcnt lgkmcnt(1)
	v_mfma_f32_32x32x16_bf16 v[32:47], v[8:11], v[124:127], v[32:47]
	v_max_f32_e32 v8, v112, v112
	v_max_f32_e32 v0, v0, v8
	v_cmp_lt_f32_e32 vcc, s93, v0
	s_waitcnt lgkmcnt(0)
	v_mfma_f32_32x32x16_bf16 v[16:31], v[140:143], v[124:127], v[16:31]
	s_cbranch_vccz .LBB0_655
	v_max_f32_e32 v0, v0, v0
	v_max_f32_e32 v8, 0, v0
	v_exp_f32_e64 v0, -v8
	v_add_f32_e32 v169, v169, v8
	v_sub_f32_e32 v111, v111, v8
	v_sub_f32_e32 v110, v110, v8
	v_pk_mul_f32 v[78:79], v[78:79], v[0:1] op_sel_hi:[1,0]
	v_pk_mul_f32 v[76:77], v[76:77], v[0:1] op_sel_hi:[1,0]
	v_pk_mul_f32 v[74:75], v[74:75], v[0:1] op_sel_hi:[1,0]
	v_pk_mul_f32 v[72:73], v[72:73], v[0:1] op_sel_hi:[1,0]
	v_pk_mul_f32 v[70:71], v[70:71], v[0:1] op_sel_hi:[1,0]
	v_pk_mul_f32 v[68:69], v[68:69], v[0:1] op_sel_hi:[1,0]
	v_pk_mul_f32 v[66:67], v[66:67], v[0:1] op_sel_hi:[1,0]
	v_pk_mul_f32 v[64:65], v[64:65], v[0:1] op_sel_hi:[1,0]
	v_pk_mul_f32 v[62:63], v[62:63], v[0:1] op_sel_hi:[1,0]
	v_pk_mul_f32 v[60:61], v[60:61], v[0:1] op_sel_hi:[1,0]
	v_pk_mul_f32 v[58:59], v[58:59], v[0:1] op_sel_hi:[1,0]
	v_pk_mul_f32 v[56:57], v[56:57], v[0:1] op_sel_hi:[1,0]
	v_pk_mul_f32 v[54:55], v[54:55], v[0:1] op_sel_hi:[1,0]
	v_pk_mul_f32 v[52:53], v[52:53], v[0:1] op_sel_hi:[1,0]
	v_pk_mul_f32 v[50:51], v[50:51], v[0:1] op_sel_hi:[1,0]
	v_pk_mul_f32 v[48:49], v[48:49], v[0:1] op_sel_hi:[1,0]
	v_pk_mul_f32 v[46:47], v[0:1], v[46:47] op_sel_hi:[0,1]
	v_pk_mul_f32 v[44:45], v[0:1], v[44:45] op_sel_hi:[0,1]
	v_pk_mul_f32 v[42:43], v[0:1], v[42:43] op_sel_hi:[0,1]
	v_pk_mul_f32 v[40:41], v[0:1], v[40:41] op_sel_hi:[0,1]
	v_pk_mul_f32 v[38:39], v[0:1], v[38:39] op_sel_hi:[0,1]
	v_pk_mul_f32 v[36:37], v[0:1], v[36:37] op_sel_hi:[0,1]
	v_pk_mul_f32 v[34:35], v[0:1], v[34:35] op_sel_hi:[0,1]
	v_pk_mul_f32 v[32:33], v[0:1], v[32:33] op_sel_hi:[0,1]
	v_pk_mul_f32 v[30:31], v[0:1], v[30:31] op_sel_hi:[0,1]
	v_pk_mul_f32 v[28:29], v[0:1], v[28:29] op_sel_hi:[0,1]
	v_pk_mul_f32 v[26:27], v[0:1], v[26:27] op_sel_hi:[0,1]
	v_pk_mul_f32 v[24:25], v[0:1], v[24:25] op_sel_hi:[0,1]
	v_pk_mul_f32 v[22:23], v[0:1], v[22:23] op_sel_hi:[0,1]
	v_pk_mul_f32 v[20:21], v[0:1], v[20:21] op_sel_hi:[0,1]
	v_pk_mul_f32 v[18:19], v[0:1], v[18:19] op_sel_hi:[0,1]
	v_pk_mul_f32 v[16:17], v[0:1], v[16:17] op_sel_hi:[0,1]
	v_sub_f32_e32 v109, v109, v8
	v_sub_f32_e32 v108, v108, v8
	v_sub_f32_e32 v107, v107, v8
	v_sub_f32_e32 v106, v106, v8
	v_sub_f32_e32 v105, v105, v8
	v_sub_f32_e32 v104, v104, v8
	v_sub_f32_e32 v103, v103, v8
	v_sub_f32_e32 v102, v102, v8
	v_sub_f32_e32 v101, v101, v8
	v_sub_f32_e32 v100, v100, v8
	v_sub_f32_e32 v99, v99, v8
	v_sub_f32_e32 v98, v98, v8
	v_sub_f32_e32 v97, v97, v8
	v_sub_f32_e32 v96, v96, v8
	v_sub_f32_e32 v95, v95, v8
	v_sub_f32_e32 v94, v94, v8
	v_sub_f32_e32 v93, v93, v8
	v_sub_f32_e32 v92, v92, v8
	v_sub_f32_e32 v91, v91, v8
	v_sub_f32_e32 v90, v90, v8
	v_sub_f32_e32 v89, v89, v8
	v_sub_f32_e32 v88, v88, v8
	v_sub_f32_e32 v87, v87, v8
	v_sub_f32_e32 v86, v86, v8
	v_sub_f32_e32 v85, v85, v8
	v_sub_f32_e32 v84, v84, v8
	v_sub_f32_e32 v83, v83, v8
	v_sub_f32_e32 v82, v82, v8
	v_sub_f32_e32 v81, v81, v8
	v_sub_f32_e32 v80, v80, v8
	v_mul_f32_e32 v184, v184, v0
